# RESID GEMM K-loop: LDS-DMA loads also in scalar-base + lane-offset form (half-tile and k-step folded into precomputed lane offsets, 4 SALU + 16 VALU fewer per iteration)
# speedup vs baseline: 1.0085x; 1.0004x over previous
; #define PG8_WAIT_V(n) asm volatile("s_waitcnt vmcnt(" #n ")" ::: "memory")
; #define PG8_BAR __builtin_amdgcn_s_barrier()
; template <int EPI, bool ALIGN_EPI = true, bool SP2 = true>
; DI void gemm8_phase(const GemmArgs& g, char* lds_) {
;     ...
;   f32x4 acc[2][2][4][2];
; #pragma unroll
;   for (int a = 0; a < 2; ++a)
; #pragma unroll
;     for (int b = 0; b < 2; ++b)
; #pragma unroll
;       for (int m = 0; m < 4; ++m)
; #pragma unroll
;         for (int n = 0; n < 2; ++n) acc[a][b][m][n] = f32x4{0.f, 0.f, 0.f, 0.f};
;   bf16x8 At[4][2], B0[2][2], B1[2][2];
;   const char* cA = (const char*)g.A0 + (size_t)cpm * tstep;
;   const char* cB = (const char*)g.Bt0 + (size_t)cpn * tstep;
;   PG8_WAIT_V(0);
;   __syncthreads();
;   if constexpr (SP2) {
;     PG8_STAGE(PG8_SB(0, 0), cB); PG8_STAGE(PG8_SB(0, 1), cB + hstep); PG8_STAGE(PG8_SA(0, 0), cA); PG8_STAGE(PG8_SA(0, 1), cA + hstep);
;     if (wr == 1) PG8_BAR;
;     PG8_WAIT_V(2); PG8_BAR;
;     PG8_STAGE(PG8_SB(1, 0), cB + kstep); PG8_STAGE(PG8_SA(1, 0), cA + kstep); PG8_STAGE(PG8_SB(1, 1), cB + hstep + kstep);
;     PG8_WAIT_V(6); PG8_BAR;
;   } else {
;     PG8_STAGE(PG8_SB(0, 0), cB); PG8_STAGE(PG8_SA(0, 0), cA); PG8_STAGE(PG8_SB(0, 1), cB + hstep); PG8_STAGE(PG8_SA(0, 1), cA + hstep);
;     if (wr == 1) PG8_BAR;
;     PG8_WAIT_V(4); PG8_BAR;
;     PG8_STAGE(PG8_SB(1, 0), cB + kstep); PG8_STAGE(PG8_SA(1, 0), cA + kstep); PG8_STAGE(PG8_SB(1, 1), cB + hstep + kstep);
;     PG8_WAIT_V(6); PG8_BAR;
;   }
;   for (;;) {
;     const int nid = (int)blockIdx.x + (ui + 1) * G;
;     const bool has_next = nid < total;
;     if (has_next) tile_map(nid, g.NTm, g.NTn, npm, npn, g.gm);
;     const char* nA = has_next ? (const char*)g.A0 + (size_t)npm * tstep : cA;
;     const char* nB = has_next ? (const char*)g.Bt0 + (size_t)npn * tstep : cB;
; #pragma unroll 1
;     for (int t = 0; t < nt; t += 2) {
;       const bool last = (t == nt - 2);
;       const char* a1 = cA + (size_t)(t + 1) * kstep;
;       const char* a2 = last ? nA : cA + (size_t)(t + 2) * kstep;
;       const char* b2 = last ? nB : cB + (size_t)(t + 2) * kstep;
;       const char* a3 = a2 + kstep; const char* b3 = b2 + kstep;
;       if constexpr (SP2) {
;         const bool relax = EPI_VM > 0 && t == 0 && ui > 0;
;         PG8_LDB(B0, 0, 0); PG8_LDB(B1, 0, 1); PG8_SCHED; PG8_LDA(At, 0, 0); PG8_STAGE(PG8_SA(1, 1), a1 + hstep);
.LBB0_1054:
	s_add_u32 s48, s48, 0x80
	s_addc_u32 s49, s49, 0
	s_add_u32 vcc_lo, s62, 0x100
	v_mov_b32_e32 v2, 0
	s_addc_u32 vcc_hi, s63, 0
	s_mov_b32 s62, 0
	v_mov_b32_e32 v3, v2
	v_mov_b32_e32 v4, v2
	v_mov_b32_e32 v5, v2
	v_mov_b32_e32 v6, v2
	v_mov_b32_e32 v7, v2
	v_mov_b32_e32 v8, v2
	v_mov_b32_e32 v9, v2
	v_mov_b32_e32 v10, v2
	v_mov_b32_e32 v11, v2
	v_mov_b32_e32 v12, v2
	v_mov_b32_e32 v13, v2
	v_mov_b32_e32 v14, v2
	v_mov_b32_e32 v15, v2
	v_mov_b32_e32 v16, v2
	v_mov_b32_e32 v17, v2
	v_mov_b32_e32 v18, v2
	v_mov_b32_e32 v19, v2
	v_mov_b32_e32 v20, v2
	v_mov_b32_e32 v21, v2
	v_mov_b32_e32 v22, v2
	v_mov_b32_e32 v23, v2
	v_mov_b32_e32 v24, v2
	v_mov_b32_e32 v25, v2
	v_mov_b32_e32 v26, v2
	v_mov_b32_e32 v27, v2
	v_mov_b32_e32 v28, v2
	v_mov_b32_e32 v29, v2
	v_mov_b32_e32 v30, v2
	v_mov_b32_e32 v31, v2
	v_mov_b32_e32 v32, v2
	v_mov_b32_e32 v33, v2
	v_mov_b32_e32 v34, v2
	v_mov_b32_e32 v35, v2
	v_mov_b32_e32 v36, v2
	v_mov_b32_e32 v37, v2
	v_mov_b32_e32 v38, v2
	v_mov_b32_e32 v39, v2
	v_mov_b32_e32 v40, v2
	v_mov_b32_e32 v41, v2
	v_mov_b32_e32 v42, v2
	v_mov_b32_e32 v43, v2
	v_mov_b32_e32 v44, v2
	v_mov_b32_e32 v45, v2
	v_mov_b32_e32 v46, v2
	v_mov_b32_e32 v47, v2
	v_mov_b32_e32 v48, v2
	v_mov_b32_e32 v49, v2
	v_mov_b32_e32 v50, v2
	v_mov_b32_e32 v51, v2
	v_mov_b32_e32 v52, v2
	v_mov_b32_e32 v53, v2
	v_mov_b32_e32 v54, v2
	v_mov_b32_e32 v55, v2
	v_mov_b32_e32 v56, v2
	v_mov_b32_e32 v57, v2
	v_mov_b32_e32 v58, v2
	v_mov_b32_e32 v59, v2
	v_mov_b32_e32 v60, v2
	v_mov_b32_e32 v61, v2
	v_mov_b32_e32 v62, v2
	v_mov_b32_e32 v63, v2
	v_mov_b32_e32 v64, v2
	v_mov_b32_e32 v65, v2
	v_mov_b32_e32 v66, v2
	v_mov_b32_e32 v67, v2
	v_mov_b32_e32 v68, v2
	v_mov_b32_e32 v69, v2
	v_mov_b32_e32 v70, v2
	v_mov_b32_e32 v71, v2
	v_mov_b32_e32 v72, v2
	v_mov_b32_e32 v73, v2
	v_mov_b32_e32 v74, v2
	v_mov_b32_e32 v75, v2
	v_mov_b32_e32 v76, v2
	v_mov_b32_e32 v77, v2
	v_mov_b32_e32 v78, v2
	v_mov_b32_e32 v79, v2
	v_mov_b32_e32 v80, v2
	v_mov_b32_e32 v81, v2
	v_mov_b32_e32 v82, v2
	v_mov_b32_e32 v83, v2
	v_mov_b32_e32 v84, v2
	v_mov_b32_e32 v85, v2
	v_mov_b32_e32 v86, v2
	v_mov_b32_e32 v87, v2
	v_mov_b32_e32 v88, v2
	v_mov_b32_e32 v89, v2
	v_mov_b32_e32 v90, v2
	v_mov_b32_e32 v91, v2
	v_mov_b32_e32 v92, v2
	v_mov_b32_e32 v93, v2
	v_mov_b32_e32 v94, v2
	v_mov_b32_e32 v95, v2
	v_mov_b32_e32 v96, v2
	v_mov_b32_e32 v97, v2
	v_mov_b32_e32 v98, v2
	v_mov_b32_e32 v99, v2
	v_mov_b32_e32 v100, v2
	v_mov_b32_e32 v101, v2
	v_mov_b32_e32 v102, v2
	v_mov_b32_e32 v103, v2
	v_mov_b32_e32 v104, v2
	v_mov_b32_e32 v105, v2
	v_mov_b32_e32 v106, v2
	v_mov_b32_e32 v107, v2
	v_mov_b32_e32 v108, v2
	v_mov_b32_e32 v109, v2
	v_mov_b32_e32 v110, v2
	v_mov_b32_e32 v111, v2
	v_mov_b32_e32 v112, v2
	v_mov_b32_e32 v113, v2
	v_mov_b32_e32 v114, v2
	v_mov_b32_e32 v115, v2
	v_mov_b32_e32 v116, v2
	v_mov_b32_e32 v117, v2
	v_mov_b32_e32 v118, v2
	v_mov_b32_e32 v119, v2
	v_mov_b32_e32 v120, v2
	v_mov_b32_e32 v121, v2
	v_mov_b32_e32 v122, v2
	v_mov_b32_e32 v123, v2
	v_mov_b32_e32 v124, v2
	v_mov_b32_e32 v125, v2
	v_mov_b32_e32 v126, v2
	v_mov_b32_e32 v127, v2
	v_mov_b32_e32 v128, v2
	v_mov_b32_e32 v129, v2
	v_add_u32_e32 v226, 0x80, v0
	v_add_u32_e32 v227, 0x80, v164
	v_add_u32_e32 v228, s28, v0
	v_add_u32_e32 v229, s28, v164
	v_add_u32_e32 v230, s28, v226
	v_add_u32_e32 v231, s28, v227
.LBB0_1055:
	v_or_b32_e32 v130, 0x10000, v191
	v_add_u32_e32 v134, 0x10400, v191
	v_add_u32_e32 v138, 0x10800, v191
	v_add_u32_e32 v142, 0x10c00, v191
	v_or_b32_e32 v146, 0x14000, v191
	v_add_u32_e32 v150, 0x14400, v191
	v_add_u32_e32 v154, 0x14800, v191
	v_add_u32_e32 v158, 0x14c00, v191
	s_add_i32 s24, s62, 2
	ds_read_b128 v[130:133], v130
	ds_read_b128 v[134:137], v134
	ds_read_b128 v[138:141], v138
	ds_read_b128 v[142:145], v142
	ds_read_b128 v[146:149], v146
	ds_read_b128 v[150:153], v150
	ds_read_b128 v[154:157], v154
	ds_read_b128 v[158:161], v158
	s_add_u32 s25, s48, 0x80
	s_addc_u32 s26, s49, 0
	s_cmp_eq_u32 s87, s62
	s_cselect_b32 s62, s44, s25
	s_cselect_b32 s63, s45, s26
	s_cselect_b32 s27, s47, vcc_hi
	s_cselect_b32 s26, s46, vcc_lo
	s_add_i32 m0, s13, 0xc000
	ds_read_b128 v[194:197], v192
	ds_read_b128 v[198:201], v192 offset:1024
	ds_read_b128 v[202:205], v192 offset:2048
	ds_read_b128 v[206:209], v192 offset:3072
	ds_read_b128 v[210:213], v192 offset:4096
	ds_read_b128 v[214:217], v192 offset:5120
	ds_read_b128 v[218:221], v192 offset:6144
	ds_read_b128 v[222:225], v192 offset:7168
	global_load_lds_dwordx4 v168, s[48:49]
	s_add_i32 m0, s13, 0xe000
	s_nop 0
	global_load_lds_dwordx4 v170, s[48:49]
	s_waitcnt vmcnt(8)
	s_waitcnt lgkmcnt(0)
	s_barrier
; #define PG8_STAGE(bufoff, gbase) do { _Pragma("unroll") for (int _i = 0; _i < 2; ++_i) \
;     __builtin_amdgcn_global_load_lds((const unsigned*)((const char*)(gbase) + voff[_i]), (LAS unsigned*)(lds + (bufoff) + ldsw + _i * 8192), 16, 0, 0); } while (0)
; #define PG8_LDA(dst, b, h) do { _Pragma("unroll") for (int m = 0; m < 4; ++m) _Pragma("unroll") for (int k = 0; k < 2; ++k) dst[m][k] = *(const LAS bf16x8*)(lds + PG8_SA(b, h) + aoff + m * 2048 + k * 1024); } while (0)
; #define PG8_WAIT_V(n) asm volatile("s_waitcnt vmcnt(" #n ")" ::: "memory")
; #define PG8_WAIT_L(n) asm volatile("s_waitcnt lgkmcnt(" #n ")" ::: "memory")
; #define PG8_BAR __builtin_amdgcn_s_barrier()
; #define PG8_SCHED __builtin_amdgcn_sched_barrier(0)
; template <int EPI, bool ALIGN_EPI = true, bool SP2 = true>
; DI void gemm8_phase(const GemmArgs& g, char* lds_) {
;     ...
;         PG8_WAIT_L(0); PG8_BAR; PG8_MMA(0, 0, At, B0); PG8_MMA(0, 1, At, B1); PG8_BAR; PG8_SCHED;
;         PG8_LDA(At, 0, 1); PG8_STAGE(PG8_SB(0, 0), b2); PG8_STAGE(PG8_SB(0, 1), b2 + hstep); PG8_STAGE(PG8_SA(0, 0), a2);
;         if (relax) PG8_WAIT_V(24); else PG8_WAIT_V(8);
;         PG8_WAIT_L(0); PG8_BAR; PG8_MMA(1, 0, At, B0); PG8_MMA(1, 1, At, B1); PG8_BAR; PG8_SCHED;
	s_setprio 1
	s_waitcnt lgkmcnt(0)
	v_mfma_f32_16x16x32_bf16 v[126:129], v[130:133], v[194:197], v[126:129]
	v_mfma_f32_16x16x32_bf16 v[122:125], v[138:141], v[194:197], v[122:125]
	v_mfma_f32_16x16x32_bf16 v[118:121], v[130:133], v[202:205], v[118:121]
	v_mfma_f32_16x16x32_bf16 v[114:117], v[138:141], v[202:205], v[114:117]
	v_mfma_f32_16x16x32_bf16 v[110:113], v[130:133], v[210:213], v[110:113]
	v_mfma_f32_16x16x32_bf16 v[106:109], v[138:141], v[210:213], v[106:109]
	v_mfma_f32_16x16x32_bf16 v[102:105], v[130:133], v[218:221], v[102:105]
	v_mfma_f32_16x16x32_bf16 v[98:101], v[138:141], v[218:221], v[98:101]
	v_mfma_f32_16x16x32_bf16 v[126:129], v[134:137], v[198:201], v[126:129]
	v_mfma_f32_16x16x32_bf16 v[122:125], v[142:145], v[198:201], v[122:125]
	v_mfma_f32_16x16x32_bf16 v[118:121], v[134:137], v[206:209], v[118:121]
	v_mfma_f32_16x16x32_bf16 v[114:117], v[142:145], v[206:209], v[114:117]
	v_mfma_f32_16x16x32_bf16 v[110:113], v[134:137], v[214:217], v[110:113]
	v_mfma_f32_16x16x32_bf16 v[106:109], v[142:145], v[214:217], v[106:109]
	v_mfma_f32_16x16x32_bf16 v[102:105], v[134:137], v[222:225], v[102:105]
	v_mfma_f32_16x16x32_bf16 v[98:101], v[142:145], v[222:225], v[98:101]
	s_setprio 0
	s_setprio 1
	v_mfma_f32_16x16x32_bf16 v[94:97], v[146:149], v[194:197], v[94:97]
	v_mfma_f32_16x16x32_bf16 v[90:93], v[154:157], v[194:197], v[90:93]
	v_mfma_f32_16x16x32_bf16 v[86:89], v[146:149], v[202:205], v[86:89]
	v_mfma_f32_16x16x32_bf16 v[82:85], v[154:157], v[202:205], v[82:85]
	v_mfma_f32_16x16x32_bf16 v[78:81], v[146:149], v[210:213], v[78:81]
	v_mfma_f32_16x16x32_bf16 v[74:77], v[154:157], v[210:213], v[74:77]
	v_mfma_f32_16x16x32_bf16 v[70:73], v[146:149], v[218:221], v[70:73]
	v_mfma_f32_16x16x32_bf16 v[66:69], v[154:157], v[218:221], v[66:69]
	v_mfma_f32_16x16x32_bf16 v[94:97], v[150:153], v[198:201], v[94:97]
	v_mfma_f32_16x16x32_bf16 v[90:93], v[158:161], v[198:201], v[90:93]
	v_mfma_f32_16x16x32_bf16 v[86:89], v[150:153], v[206:209], v[86:89]
	v_mfma_f32_16x16x32_bf16 v[82:85], v[158:161], v[206:209], v[82:85]
	v_mfma_f32_16x16x32_bf16 v[78:81], v[150:153], v[214:217], v[78:81]
	v_mfma_f32_16x16x32_bf16 v[74:77], v[158:161], v[214:217], v[74:77]
	v_mfma_f32_16x16x32_bf16 v[70:73], v[150:153], v[222:225], v[70:73]
	v_mfma_f32_16x16x32_bf16 v[66:69], v[158:161], v[222:225], v[66:69]
	s_setprio 0
	s_barrier
	s_mov_b32 m0, s14
	ds_read_b128 v[194:197], v192 offset:16384
	ds_read_b128 v[198:201], v192 offset:17408
	ds_read_b128 v[202:205], v192 offset:18432
	ds_read_b128 v[206:209], v192 offset:19456
	ds_read_b128 v[210:213], v192 offset:20480
	ds_read_b128 v[214:217], v192 offset:21504
	ds_read_b128 v[218:221], v192 offset:22528
	ds_read_b128 v[222:225], v192 offset:23552
	global_load_lds_dwordx4 v0, s[26:27]
	s_mov_b32 m0, s15
	s_nop 0
	global_load_lds_dwordx4 v164, s[26:27]
	s_mov_b32 m0, s16
	s_nop 0
	global_load_lds_dwordx4 v228, s[26:27]
	s_mov_b32 m0, s17
	s_nop 0
	global_load_lds_dwordx4 v229, s[26:27]
	s_mov_b32 m0, s13
	s_nop 0
	global_load_lds_dwordx4 v0, s[62:63]
	s_mov_b32 m0, s18
	s_nop 0
	global_load_lds_dwordx4 v164, s[62:63]
	s_waitcnt vmcnt(8)
	s_waitcnt lgkmcnt(0)
	s_barrier
	s_setprio 1
	s_waitcnt lgkmcnt(0)
	v_mfma_f32_16x16x32_bf16 v[62:65], v[130:133], v[194:197], v[62:65]
	v_mfma_f32_16x16x32_bf16 v[58:61], v[138:141], v[194:197], v[58:61]
	v_mfma_f32_16x16x32_bf16 v[54:57], v[130:133], v[202:205], v[54:57]
	v_mfma_f32_16x16x32_bf16 v[50:53], v[138:141], v[202:205], v[50:53]
	v_mfma_f32_16x16x32_bf16 v[46:49], v[130:133], v[210:213], v[46:49]
	v_mfma_f32_16x16x32_bf16 v[42:45], v[138:141], v[210:213], v[42:45]
	v_mfma_f32_16x16x32_bf16 v[38:41], v[130:133], v[218:221], v[38:41]
	v_mfma_f32_16x16x32_bf16 v[34:37], v[138:141], v[218:221], v[34:37]
	v_mfma_f32_16x16x32_bf16 v[62:65], v[134:137], v[198:201], v[62:65]
	v_mfma_f32_16x16x32_bf16 v[58:61], v[142:145], v[198:201], v[58:61]
	v_mfma_f32_16x16x32_bf16 v[54:57], v[134:137], v[206:209], v[54:57]
	v_mfma_f32_16x16x32_bf16 v[50:53], v[142:145], v[206:209], v[50:53]
	v_mfma_f32_16x16x32_bf16 v[46:49], v[134:137], v[214:217], v[46:49]
	v_mfma_f32_16x16x32_bf16 v[42:45], v[142:145], v[214:217], v[42:45]
	v_mfma_f32_16x16x32_bf16 v[38:41], v[134:137], v[222:225], v[38:41]
	v_mfma_f32_16x16x32_bf16 v[34:37], v[142:145], v[222:225], v[34:37]
	s_setprio 0
	s_setprio 1
	v_mfma_f32_16x16x32_bf16 v[30:33], v[146:149], v[194:197], v[30:33]
	v_mfma_f32_16x16x32_bf16 v[26:29], v[154:157], v[194:197], v[26:29]
	v_mfma_f32_16x16x32_bf16 v[22:25], v[146:149], v[202:205], v[22:25]
	v_mfma_f32_16x16x32_bf16 v[18:21], v[154:157], v[202:205], v[18:21]
	v_mfma_f32_16x16x32_bf16 v[14:17], v[146:149], v[210:213], v[14:17]
	v_mfma_f32_16x16x32_bf16 v[10:13], v[154:157], v[210:213], v[10:13]
	v_mfma_f32_16x16x32_bf16 v[6:9], v[146:149], v[218:221], v[6:9]
	v_mfma_f32_16x16x32_bf16 v[2:5], v[154:157], v[218:221], v[2:5]
	v_mfma_f32_16x16x32_bf16 v[30:33], v[150:153], v[198:201], v[30:33]
	v_mfma_f32_16x16x32_bf16 v[26:29], v[158:161], v[198:201], v[26:29]
	v_mfma_f32_16x16x32_bf16 v[22:25], v[150:153], v[206:209], v[22:25]
	v_mfma_f32_16x16x32_bf16 v[18:21], v[158:161], v[206:209], v[18:21]
	v_mfma_f32_16x16x32_bf16 v[14:17], v[150:153], v[214:217], v[14:17]
	v_mfma_f32_16x16x32_bf16 v[10:13], v[158:161], v[214:217], v[10:13]
	v_mfma_f32_16x16x32_bf16 v[6:9], v[150:153], v[222:225], v[6:9]
	v_mfma_f32_16x16x32_bf16 v[2:5], v[158:161], v[222:225], v[2:5]
	s_setprio 0
	s_barrier
; #define PG8_STAGE(bufoff, gbase) do { _Pragma("unroll") for (int _i = 0; _i < 2; ++_i) \
;     __builtin_amdgcn_global_load_lds((const unsigned*)((const char*)(gbase) + voff[_i]), (LAS unsigned*)(lds + (bufoff) + ldsw + _i * 8192), 16, 0, 0); } while (0)
; #define PG8_LDA(dst, b, h) do { _Pragma("unroll") for (int m = 0; m < 4; ++m) _Pragma("unroll") for (int k = 0; k < 2; ++k) dst[m][k] = *(const LAS bf16x8*)(lds + PG8_SA(b, h) + aoff + m * 2048 + k * 1024); } while (0)
; #define PG8_LDB(dst, b, h) do { _Pragma("unroll") for (int n = 0; n < 2; ++n) _Pragma("unroll") for (int k = 0; k < 2; ++k) dst[n][k] = *(const LAS bf16x8*)(lds + PG8_SB(b, h) + boff + n * 2048 + k * 1024); } while (0)
; #define PG8_WAIT_V(n) asm volatile("s_waitcnt vmcnt(" #n ")" ::: "memory")
; #define PG8_WAIT_L(n) asm volatile("s_waitcnt lgkmcnt(" #n ")" ::: "memory")
; #define PG8_BAR __builtin_amdgcn_s_barrier()
; #define PG8_SCHED __builtin_amdgcn_sched_barrier(0)
; template <int EPI, bool ALIGN_EPI = true, bool SP2 = true>
; DI void gemm8_phase(const GemmArgs& g, char* lds_) {
;     ...
;         PG8_LDB(B0, 1, 0); PG8_LDB(B1, 1, 1); PG8_SCHED; PG8_LDA(At, 1, 0); PG8_STAGE(PG8_SA(0, 1), a2 + hstep);
;         PG8_WAIT_V(8); PG8_WAIT_L(0); PG8_BAR; PG8_MMA(0, 0, At, B0); PG8_MMA(0, 1, At, B1); PG8_BAR; PG8_SCHED;
;         PG8_LDA(At, 1, 1); PG8_STAGE(PG8_SB(1, 0), b3); PG8_STAGE(PG8_SB(1, 1), b3 + hstep); PG8_STAGE(PG8_SA(1, 0), a3);
;         PG8_WAIT_V(8); PG8_WAIT_L(0); PG8_BAR; PG8_MMA(1, 0, At, B0); PG8_MMA(1, 1, At, B1); PG8_BAR; PG8_SCHED;
	v_or_b32_e32 v130, 0x18000, v191
	v_add_u32_e32 v134, 0x18400, v191
	v_add_u32_e32 v138, 0x18800, v191
	v_add_u32_e32 v142, 0x18c00, v191
	v_or_b32_e32 v146, 0x1c000, v191
	v_add_u32_e32 v150, 0x1c400, v191
	v_add_u32_e32 v154, 0x1c800, v191
	v_add_u32_e32 v158, 0x1cc00, v191
	ds_read_b128 v[130:133], v130
	ds_read_b128 v[134:137], v134
	ds_read_b128 v[138:141], v138
	ds_read_b128 v[142:145], v142
	ds_read_b128 v[146:149], v146
	ds_read_b128 v[150:153], v150
	ds_read_b128 v[154:157], v154
	ds_read_b128 v[158:161], v158
	s_mov_b32 m0, s19
	ds_read_b128 v[194:197], v192 offset:32768
	ds_read_b128 v[198:201], v192 offset:33792
	ds_read_b128 v[202:205], v192 offset:34816
	ds_read_b128 v[206:209], v192 offset:35840
	ds_read_b128 v[210:213], v192 offset:36864
	ds_read_b128 v[214:217], v192 offset:37888
	ds_read_b128 v[218:221], v192 offset:38912
	ds_read_b128 v[222:225], v192 offset:39936
	global_load_lds_dwordx4 v228, s[62:63]
	s_mov_b32 m0, s20
	s_nop 0
	global_load_lds_dwordx4 v229, s[62:63]
	s_waitcnt vmcnt(8)
	s_waitcnt lgkmcnt(0)
	s_barrier
	s_setprio 1
	s_waitcnt lgkmcnt(0)
	v_mfma_f32_16x16x32_bf16 v[126:129], v[130:133], v[194:197], v[126:129]
	v_mfma_f32_16x16x32_bf16 v[122:125], v[138:141], v[194:197], v[122:125]
	v_mfma_f32_16x16x32_bf16 v[118:121], v[130:133], v[202:205], v[118:121]
	v_mfma_f32_16x16x32_bf16 v[114:117], v[138:141], v[202:205], v[114:117]
	v_mfma_f32_16x16x32_bf16 v[110:113], v[130:133], v[210:213], v[110:113]
	v_mfma_f32_16x16x32_bf16 v[106:109], v[138:141], v[210:213], v[106:109]
	v_mfma_f32_16x16x32_bf16 v[102:105], v[130:133], v[218:221], v[102:105]
	v_mfma_f32_16x16x32_bf16 v[98:101], v[138:141], v[218:221], v[98:101]
	v_mfma_f32_16x16x32_bf16 v[126:129], v[134:137], v[198:201], v[126:129]
	v_mfma_f32_16x16x32_bf16 v[122:125], v[142:145], v[198:201], v[122:125]
	v_mfma_f32_16x16x32_bf16 v[118:121], v[134:137], v[206:209], v[118:121]
	v_mfma_f32_16x16x32_bf16 v[114:117], v[142:145], v[206:209], v[114:117]
	v_mfma_f32_16x16x32_bf16 v[110:113], v[134:137], v[214:217], v[110:113]
	v_mfma_f32_16x16x32_bf16 v[106:109], v[142:145], v[214:217], v[106:109]
	v_mfma_f32_16x16x32_bf16 v[102:105], v[134:137], v[222:225], v[102:105]
	v_mfma_f32_16x16x32_bf16 v[98:101], v[142:145], v[222:225], v[98:101]
	s_setprio 0
	s_setprio 1
	v_mfma_f32_16x16x32_bf16 v[94:97], v[146:149], v[194:197], v[94:97]
	v_mfma_f32_16x16x32_bf16 v[90:93], v[154:157], v[194:197], v[90:93]
	v_mfma_f32_16x16x32_bf16 v[86:89], v[146:149], v[202:205], v[86:89]
	v_mfma_f32_16x16x32_bf16 v[82:85], v[154:157], v[202:205], v[82:85]
	v_mfma_f32_16x16x32_bf16 v[78:81], v[146:149], v[210:213], v[78:81]
	v_mfma_f32_16x16x32_bf16 v[74:77], v[154:157], v[210:213], v[74:77]
	v_mfma_f32_16x16x32_bf16 v[70:73], v[146:149], v[218:221], v[70:73]
	v_mfma_f32_16x16x32_bf16 v[66:69], v[154:157], v[218:221], v[66:69]
	v_mfma_f32_16x16x32_bf16 v[94:97], v[150:153], v[198:201], v[94:97]
	v_mfma_f32_16x16x32_bf16 v[90:93], v[158:161], v[198:201], v[90:93]
	v_mfma_f32_16x16x32_bf16 v[86:89], v[150:153], v[206:209], v[86:89]
	v_mfma_f32_16x16x32_bf16 v[82:85], v[158:161], v[206:209], v[82:85]
	v_mfma_f32_16x16x32_bf16 v[78:81], v[150:153], v[214:217], v[78:81]
	v_mfma_f32_16x16x32_bf16 v[74:77], v[158:161], v[214:217], v[74:77]
	v_mfma_f32_16x16x32_bf16 v[70:73], v[150:153], v[222:225], v[70:73]
	v_mfma_f32_16x16x32_bf16 v[66:69], v[158:161], v[222:225], v[66:69]
	s_setprio 0
	s_barrier
	s_mov_b32 m0, s51
	ds_read_b128 v[194:197], v192 offset:49152
	ds_read_b128 v[198:201], v192 offset:50176
	ds_read_b128 v[202:205], v192 offset:51200
	ds_read_b128 v[206:209], v192 offset:52224
	ds_read_b128 v[210:213], v192 offset:53248
	ds_read_b128 v[214:217], v192 offset:54272
	ds_read_b128 v[218:221], v192 offset:55296
	ds_read_b128 v[222:225], v192 offset:56320
	global_load_lds_dwordx4 v226, s[26:27]
	s_mov_b32 m0, s57
	s_nop 0
	global_load_lds_dwordx4 v227, s[26:27]
	s_mov_b32 m0, s84
	s_nop 0
	global_load_lds_dwordx4 v230, s[26:27]
	s_mov_b32 m0, s85
	s_nop 0
	global_load_lds_dwordx4 v231, s[26:27]
	s_mov_b32 m0, s68
	s_nop 0
	global_load_lds_dwordx4 v226, s[62:63]
	s_mov_b32 m0, s69
	s_nop 0
	global_load_lds_dwordx4 v227, s[62:63]
	s_waitcnt vmcnt(8)
	s_waitcnt lgkmcnt(0)
	s_barrier
	s_setprio 1
	s_waitcnt lgkmcnt(0)
	v_mfma_f32_16x16x32_bf16 v[62:65], v[130:133], v[194:197], v[62:65]
	v_mfma_f32_16x16x32_bf16 v[58:61], v[138:141], v[194:197], v[58:61]
	v_mfma_f32_16x16x32_bf16 v[54:57], v[130:133], v[202:205], v[54:57]
	v_mfma_f32_16x16x32_bf16 v[50:53], v[138:141], v[202:205], v[50:53]
	v_mfma_f32_16x16x32_bf16 v[46:49], v[130:133], v[210:213], v[46:49]
	v_mfma_f32_16x16x32_bf16 v[42:45], v[138:141], v[210:213], v[42:45]
	v_mfma_f32_16x16x32_bf16 v[38:41], v[130:133], v[218:221], v[38:41]
	v_mfma_f32_16x16x32_bf16 v[34:37], v[138:141], v[218:221], v[34:37]
	v_mfma_f32_16x16x32_bf16 v[62:65], v[134:137], v[198:201], v[62:65]
	v_mfma_f32_16x16x32_bf16 v[58:61], v[142:145], v[198:201], v[58:61]
	v_mfma_f32_16x16x32_bf16 v[54:57], v[134:137], v[206:209], v[54:57]
	v_mfma_f32_16x16x32_bf16 v[50:53], v[142:145], v[206:209], v[50:53]
	v_mfma_f32_16x16x32_bf16 v[46:49], v[134:137], v[214:217], v[46:49]
	v_mfma_f32_16x16x32_bf16 v[42:45], v[142:145], v[214:217], v[42:45]
	v_mfma_f32_16x16x32_bf16 v[38:41], v[134:137], v[222:225], v[38:41]
	v_mfma_f32_16x16x32_bf16 v[34:37], v[142:145], v[222:225], v[34:37]
	s_setprio 0
	s_setprio 1
	v_mfma_f32_16x16x32_bf16 v[30:33], v[146:149], v[194:197], v[30:33]
	v_mfma_f32_16x16x32_bf16 v[26:29], v[154:157], v[194:197], v[26:29]
	v_mfma_f32_16x16x32_bf16 v[22:25], v[146:149], v[202:205], v[22:25]
	v_mfma_f32_16x16x32_bf16 v[18:21], v[154:157], v[202:205], v[18:21]
	v_mfma_f32_16x16x32_bf16 v[14:17], v[146:149], v[210:213], v[14:17]
	v_mfma_f32_16x16x32_bf16 v[10:13], v[154:157], v[210:213], v[10:13]
	v_mfma_f32_16x16x32_bf16 v[6:9], v[146:149], v[218:221], v[6:9]
	v_mfma_f32_16x16x32_bf16 v[2:5], v[154:157], v[218:221], v[2:5]
	v_mfma_f32_16x16x32_bf16 v[30:33], v[150:153], v[198:201], v[30:33]
	v_mfma_f32_16x16x32_bf16 v[26:29], v[158:161], v[198:201], v[26:29]
	v_mfma_f32_16x16x32_bf16 v[22:25], v[150:153], v[206:209], v[22:25]
	v_mfma_f32_16x16x32_bf16 v[18:21], v[158:161], v[206:209], v[18:21]
	v_mfma_f32_16x16x32_bf16 v[14:17], v[150:153], v[214:217], v[14:17]
	v_mfma_f32_16x16x32_bf16 v[10:13], v[158:161], v[214:217], v[10:13]
	v_mfma_f32_16x16x32_bf16 v[6:9], v[150:153], v[222:225], v[6:9]
	v_mfma_f32_16x16x32_bf16 v[2:5], v[158:161], v[222:225], v[2:5]
	s_setprio 0
	s_barrier
; DI void gemm8_resid_epilogue(const GemmArgs& g, f32x4 (&acc)[2][2][4][2], const int brow, const int bcol, const int wr, const int wc, const int fr, const int fq) {
;     ...
;   auto base = [&](int ai, int bj) -> size_t { return (size_t)(brow + ai * 128 + wr * 64 + fr) * DM + bcol + bj * 128 + wc * 32 + fq * 4; };
;   f32x4 ra[4][2], rb[4][2];
;   auto ld = [&](f32x4 (&r)[4][2], size_t ib) {
; #pragma unroll
;     for (int m = 0; m < 4; ++m)
; #pragma unroll
;       for (int n = 0; n < 2; ++n) r[m][n] = *(const f32x4*)(src + ib + (size_t)(m * 16) * DM + n * 16);
;   };
;   auto st = [&](const f32x4 (&r)[4][2], const f32x4 (&a)[4][2], size_t ib) {
; #pragma unroll
;     for (int m = 0; m < 4; ++m)
; #pragma unroll
;       for (int n = 0; n < 2; ++n) {
;         f32x4 o;
;         o.x = r[m][n].x + sc * a[m][n][0]; o.y = r[m][n].y + sc * a[m][n][1];
;         o.z = r[m][n].z + sc * a[m][n][2]; o.w = r[m][n].w + sc * a[m][n][3];
;         *(f32x4*)(X + ib + (size_t)(m * 16) * DM + n * 16) = o;
;       }
;   };
;   const size_t b00 = base(0, 0), b01 = base(0, 1), b10 = base(1, 0), b11 = base(1, 1);
;   ld(ra, b00); ld(rb, b01);
;   st(ra, acc[0][0], b00); ld(ra, b10);
;   st(rb, acc[0][1], b01); ld(rb, b11);
;   st(ra, acc[1][0], b10);
; template <int EPI, bool ALIGN_EPI = true, bool SP2 = true>
; DI void gemm8_phase(const GemmArgs& g, char* lds_) {
;     ...
; #pragma unroll 1
;     for (int t = 0; t < nt; t += 2) {
	s_add_u32 s48, s48, 0x100
	s_addc_u32 s49, s49, 0
	s_add_u32 vcc_lo, vcc_lo, 0x100
	s_addc_u32 vcc_hi, vcc_hi, 0
	s_cmp_ge_u32 s24, s50
	s_mov_b32 s62, s24
	s_cbranch_scc0 .LBB0_1055
	s_lshl_b32 s23, s23, 8
	s_add_i32 s23, s23, s21
	s_lshl_b32 s24, s91, 8
	v_or_b32_e32 v130, s23, v163
	v_ashrrev_i32_e32 v131, 31, v130
	s_ashr_i32 s25, s24, 31
	v_lshlrev_b64 v[130:131], 10, v[130:131]
	v_mov_b32_e32 v133, s25
	v_or_b32_e32 v132, s24, v166
	v_lshl_add_u64 v[130:131], v[130:131], 0, v[132:133]
	v_add_u32_e32 v134, s23, v193
	v_ashrrev_i32_e32 v135, 31, v134
	v_lshlrev_b64 v[226:227], 2, v[130:131]
	v_lshlrev_b64 v[134:135], 10, v[134:135]
	v_lshl_add_u64 v[130:131], s[40:41], 0, v[226:227]
	v_lshl_add_u64 v[172:173], v[134:135], 0, v[132:133]
	global_load_dwordx4 v[194:197], v[130:131], off
	global_load_dwordx4 v[198:201], v[130:131], off offset:64
	v_add_co_u32_e32 v132, vcc, s89, v130
	s_mov_b32 s23, s86
	s_nop 0
	v_addc_co_u32_e32 v133, vcc, 0, v131, vcc
	global_load_dwordx4 v[202:205], v[132:133], off
	global_load_dwordx4 v[206:209], v[132:133], off offset:64
	v_add_co_u32_e32 v134, vcc, s96, v130
	s_mov_b32 s91, s22
	s_nop 0
	v_addc_co_u32_e32 v135, vcc, 0, v131, vcc
	global_load_dwordx4 v[210:213], v[134:135], off
	global_load_dwordx4 v[214:217], v[134:135], off offset:64
	v_add_co_u32_e32 v228, vcc, s94, v130
	s_mov_b64 s[62:63], s[46:47]
	s_nop 0
	v_addc_co_u32_e32 v229, vcc, 0, v131, vcc
	global_load_dwordx4 v[218:221], v[228:229], off
	global_load_dwordx4 v[222:225], v[228:229], off offset:64
	global_load_dwordx4 v[158:161], v[130:131], off offset:512
	global_load_dwordx4 v[154:157], v[130:131], off offset:576
	global_load_dwordx4 v[150:153], v[132:133], off offset:512
	global_load_dwordx4 v[146:149], v[132:133], off offset:576
	global_load_dwordx4 v[142:145], v[134:135], off offset:512
	global_load_dwordx4 v[138:141], v[134:135], off offset:576
	s_nop 0
	global_load_dwordx4 v[134:137], v[228:229], off offset:512
	global_load_dwordx4 v[130:133], v[228:229], off offset:576
	s_mov_b64 s[48:49], s[44:45]
	s_waitcnt vmcnt(0)
	v_pk_fma_f32 v[194:195], s[0:1], v[126:127], v[194:195]
	v_lshl_add_u64 v[126:127], s[72:73], 0, v[226:227]
	v_pk_fma_f32 v[124:125], s[42:43], v[124:125], v[200:201]
	v_pk_fma_f32 v[122:123], s[0:1], v[122:123], v[198:199]
	global_store_dwordx4 v[126:127], v[122:125], off offset:64
	v_pk_fma_f32 v[196:197], s[42:43], v[128:129], v[196:197]
	global_store_dwordx4 v[126:127], v[194:197], off
	v_pk_fma_f32 v[122:123], s[42:43], v[120:121], v[204:205]
	v_pk_fma_f32 v[120:121], s[0:1], v[118:119], v[202:203]
	v_add_co_u32_e32 v118, vcc, s89, v126
	v_pk_fma_f32 v[116:117], s[42:43], v[116:117], v[208:209]
	s_nop 0
	v_addc_co_u32_e32 v119, vcc, 0, v127, vcc
	v_pk_fma_f32 v[114:115], s[0:1], v[114:115], v[206:207]
	global_store_dwordx4 v[118:119], v[114:117], off offset:64
	v_pk_fma_f32 v[108:109], s[42:43], v[108:109], v[216:217]
	v_pk_fma_f32 v[106:107], s[0:1], v[106:107], v[214:215]
	v_pk_fma_f32 v[114:115], s[42:43], v[112:113], v[212:213]
	v_pk_fma_f32 v[112:113], s[0:1], v[110:111], v[210:211]
	v_add_co_u32_e32 v110, vcc, s96, v126
	v_pk_fma_f32 v[100:101], s[42:43], v[100:101], v[224:225]
	s_nop 0
	v_addc_co_u32_e32 v111, vcc, 0, v127, vcc
	global_store_dwordx4 v[110:111], v[106:109], off offset:64
	v_pk_fma_f32 v[98:99], s[0:1], v[98:99], v[222:223]
	global_store_dwordx4 v[118:119], v[120:123], off
	v_pk_fma_f32 v[106:107], s[42:43], v[104:105], v[220:221]
	v_pk_fma_f32 v[104:105], s[0:1], v[102:103], v[218:219]
	v_add_co_u32_e32 v102, vcc, s94, v126
	v_lshlrev_b64 v[108:109], 2, v[172:173]
	s_nop 0
	v_addc_co_u32_e32 v103, vcc, 0, v127, vcc
	global_store_dwordx4 v[110:111], v[112:115], off
	global_store_dwordx4 v[102:103], v[104:107], off
	global_store_dwordx4 v[102:103], v[98:101], off offset:64
	v_lshl_add_u64 v[116:117], s[40:41], 0, v[108:109]
	global_load_dwordx4 v[104:107], v[116:117], off
	global_load_dwordx4 v[112:115], v[116:117], off offset:64
	v_add_co_u32_e32 v124, vcc, s89, v116
	v_pk_fma_f32 v[96:97], s[42:43], v[96:97], v[160:161]
	s_nop 0
	v_addc_co_u32_e32 v125, vcc, 0, v117, vcc
	global_load_dwordx4 v[120:123], v[124:125], off
	global_load_dwordx4 v[194:197], v[124:125], off offset:64
	v_add_co_u32_e32 v128, vcc, s96, v116
	v_pk_fma_f32 v[94:95], s[0:1], v[94:95], v[158:159]
	s_nop 0
	v_addc_co_u32_e32 v129, vcc, 0, v117, vcc
	global_load_dwordx4 v[198:201], v[128:129], off
	global_load_dwordx4 v[202:205], v[128:129], off offset:64
	v_add_co_u32_e32 v172, vcc, s94, v116
	v_pk_fma_f32 v[92:93], s[42:43], v[92:93], v[156:157]
	s_nop 0
	v_addc_co_u32_e32 v173, vcc, 0, v117, vcc
	v_pk_fma_f32 v[90:91], s[0:1], v[90:91], v[154:155]
	v_pk_fma_f32 v[88:89], s[42:43], v[88:89], v[152:153]
	v_pk_fma_f32 v[86:87], s[0:1], v[86:87], v[150:151]
	v_pk_fma_f32 v[84:85], s[42:43], v[84:85], v[148:149]
	v_pk_fma_f32 v[82:83], s[0:1], v[82:83], v[146:147]
	v_pk_fma_f32 v[80:81], s[42:43], v[80:81], v[144:145]
	v_pk_fma_f32 v[78:79], s[0:1], v[78:79], v[142:143]
	v_pk_fma_f32 v[76:77], s[42:43], v[76:77], v[140:141]
	v_pk_fma_f32 v[74:75], s[0:1], v[74:75], v[138:139]
	v_pk_fma_f32 v[72:73], s[42:43], v[72:73], v[136:137]
	v_pk_fma_f32 v[70:71], s[0:1], v[70:71], v[134:135]
	v_pk_fma_f32 v[68:69], s[42:43], v[68:69], v[132:133]
	v_pk_fma_f32 v[66:67], s[0:1], v[66:67], v[130:131]
	global_load_dwordx4 v[206:209], v[172:173], off
	global_load_dwordx4 v[98:101], v[172:173], off offset:64
	s_waitcnt vmcnt(7)
; #define PG8_WAIT_V(n) asm volatile("s_waitcnt vmcnt(" #n ")" ::: "memory")
; #define PG8_BAR __builtin_amdgcn_s_barrier()
; DI void gemm8_resid_epilogue(const GemmArgs& g, f32x4 (&acc)[2][2][4][2], const int brow, const int bcol, const int wr, const int wc, const int fr, const int fq) {
;     ...
;   const size_t b00 = base(0, 0), b01 = base(0, 1), b10 = base(1, 0), b11 = base(1, 1);
;   ld(ra, b00); ld(rb, b01);
;   st(ra, acc[0][0], b00); ld(ra, b10);
;   st(rb, acc[0][1], b01); ld(rb, b11);
;   st(ra, acc[1][0], b10);
;   st(rb, acc[1][1], b11);
; template <int EPI, bool ALIGN_EPI = true, bool SP2 = true>
; DI void gemm8_phase(const GemmArgs& g, char* lds_) {
;     ...
;     if (!has_next) break;
; #pragma unroll
;     for (int a = 0; a < 2; ++a)
; #pragma unroll
;       for (int b = 0; b < 2; ++b)
; #pragma unroll
;         for (int m = 0; m < 4; ++m)
; #pragma unroll
;           for (int n = 0; n < 2; ++n) acc[a][b][m][n] = f32x4{0.f, 0.f, 0.f, 0.f};
;     cpm = npm; cpn = npn; cA = nA; cB = nB; ++ui;
;     if constexpr (ALIGN_EPI) { if (wr == 1) PG8_BAR; }
;   }
;   PG8_WAIT_V(0);
;   if constexpr (!ALIGN_EPI) { if (wr == 0) PG8_BAR; }
;   PG8_BAR;
	v_pk_fma_f32 v[64:65], s[42:43], v[64:65], v[106:107]
	global_store_dwordx4 v[126:127], v[94:97], off offset:512
	global_store_dwordx4 v[126:127], v[90:93], off offset:576
	global_store_dwordx4 v[118:119], v[86:89], off offset:512
	global_store_dwordx4 v[118:119], v[82:85], off offset:576
	global_store_dwordx4 v[110:111], v[78:81], off offset:512
	global_store_dwordx4 v[110:111], v[74:77], off offset:576
	global_store_dwordx4 v[102:103], v[70:73], off offset:512
	global_store_dwordx4 v[102:103], v[66:69], off offset:576
	global_load_dwordx4 v[94:97], v[116:117], off offset:512
	global_load_dwordx4 v[90:93], v[116:117], off offset:576
	global_load_dwordx4 v[86:89], v[124:125], off offset:512
	global_load_dwordx4 v[82:85], v[124:125], off offset:576
	global_load_dwordx4 v[78:81], v[128:129], off offset:512
	global_load_dwordx4 v[74:77], v[128:129], off offset:576
	global_load_dwordx4 v[70:73], v[172:173], off offset:512
	global_load_dwordx4 v[66:69], v[172:173], off offset:576
	v_lshl_add_u64 v[102:103], s[72:73], 0, v[108:109]
	s_waitcnt vmcnt(22)
	v_pk_fma_f32 v[60:61], s[42:43], v[60:61], v[114:115]
	v_pk_fma_f32 v[58:59], s[0:1], v[58:59], v[112:113]
	global_store_dwordx4 v[102:103], v[58:61], off offset:64
	s_waitcnt vmcnt(21)
	v_pk_fma_f32 v[52:53], s[42:43], v[52:53], v[196:197]
	v_pk_fma_f32 v[50:51], s[0:1], v[50:51], v[194:195]
	v_add_co_u32_e32 v58, vcc, s89, v102
	s_waitcnt vmcnt(19)
	v_pk_fma_f32 v[44:45], s[42:43], v[44:45], v[204:205]
	v_addc_co_u32_e32 v59, vcc, 0, v103, vcc
	global_store_dwordx4 v[58:59], v[50:53], off offset:64
	v_pk_fma_f32 v[42:43], s[0:1], v[42:43], v[202:203]
	v_pk_fma_f32 v[62:63], s[0:1], v[62:63], v[104:105]
	v_add_co_u32_e32 v50, vcc, s96, v102
	v_pk_fma_f32 v[56:57], s[42:43], v[56:57], v[122:123]
	s_nop 0
	v_addc_co_u32_e32 v51, vcc, 0, v103, vcc
	global_store_dwordx4 v[50:51], v[42:45], off offset:64
	v_pk_fma_f32 v[54:55], s[0:1], v[54:55], v[120:121]
	v_pk_fma_f32 v[48:49], s[42:43], v[48:49], v[200:201]
	v_add_co_u32_e32 v42, vcc, s94, v102
	v_pk_fma_f32 v[46:47], s[0:1], v[46:47], v[198:199]
	s_nop 0
	v_addc_co_u32_e32 v43, vcc, 0, v103, vcc
	s_waitcnt vmcnt(20)
	v_pk_fma_f32 v[40:41], s[42:43], v[40:41], v[208:209]
	v_pk_fma_f32 v[38:39], s[0:1], v[38:39], v[206:207]
	s_waitcnt vmcnt(19)
	v_pk_fma_f32 v[36:37], s[42:43], v[36:37], v[100:101]
	v_pk_fma_f32 v[34:35], s[0:1], v[34:35], v[98:99]
	s_and_b64 vcc, exec, s[34:35]
	global_store_dwordx4 v[102:103], v[62:65], off
	global_store_dwordx4 v[58:59], v[54:57], off
	global_store_dwordx4 v[50:51], v[46:49], off
	global_store_dwordx4 v[42:43], v[38:41], off
	global_store_dwordx4 v[42:43], v[34:37], off offset:64
	s_waitcnt vmcnt(15)
	v_pk_fma_f32 v[32:33], s[42:43], v[32:33], v[96:97]
	v_pk_fma_f32 v[30:31], s[0:1], v[30:31], v[94:95]
	s_waitcnt vmcnt(14)
	v_pk_fma_f32 v[28:29], s[42:43], v[28:29], v[92:93]
	v_pk_fma_f32 v[26:27], s[0:1], v[26:27], v[90:91]
	s_waitcnt vmcnt(13)
	v_pk_fma_f32 v[24:25], s[42:43], v[24:25], v[88:89]
	v_pk_fma_f32 v[22:23], s[0:1], v[22:23], v[86:87]
	s_waitcnt vmcnt(12)
	v_pk_fma_f32 v[20:21], s[42:43], v[20:21], v[84:85]
	v_pk_fma_f32 v[18:19], s[0:1], v[18:19], v[82:83]
	s_waitcnt vmcnt(11)
	v_pk_fma_f32 v[16:17], s[42:43], v[16:17], v[80:81]
	v_pk_fma_f32 v[14:15], s[0:1], v[14:15], v[78:79]
	s_waitcnt vmcnt(10)
	v_pk_fma_f32 v[12:13], s[42:43], v[12:13], v[76:77]
	v_pk_fma_f32 v[10:11], s[0:1], v[10:11], v[74:75]
	s_waitcnt vmcnt(9)
	v_pk_fma_f32 v[8:9], s[42:43], v[8:9], v[72:73]
	v_pk_fma_f32 v[6:7], s[0:1], v[6:7], v[70:71]
	s_waitcnt vmcnt(8)
	v_pk_fma_f32 v[4:5], s[42:43], v[4:5], v[68:69]
	v_pk_fma_f32 v[2:3], s[0:1], v[2:3], v[66:67]
	global_store_dwordx4 v[102:103], v[30:33], off offset:512
	global_store_dwordx4 v[102:103], v[26:29], off offset:576
	global_store_dwordx4 v[58:59], v[22:25], off offset:512
	global_store_dwordx4 v[58:59], v[18:21], off offset:576
	global_store_dwordx4 v[50:51], v[14:17], off offset:512
	global_store_dwordx4 v[50:51], v[10:13], off offset:576
	global_store_dwordx4 v[42:43], v[6:9], off offset:512
	global_store_dwordx4 v[42:43], v[2:5], off offset:576
	s_cbranch_vccz .LBB0_1050
	s_waitcnt vmcnt(0)
	v_readlane_b32 s64, v254, 53
	v_readlane_b32 s66, v254, 55
	v_readlane_b32 s70, v254, 59
	v_readlane_b32 s24, v254, 51
	s_cmpk_gt_u32 s5, 0xff
	v_readlane_b32 s65, v254, 54
	v_readlane_b32 s67, v254, 56
	s_mov_b32 s55, s59
	v_readlane_b32 s71, v254, 60
	v_readlane_b32 s56, v254, 61
	v_readlane_b32 s79, v254, 62
	v_readlane_b32 s20, v254, 49
	v_readlane_b32 s21, v254, 50
	v_readlane_b32 s25, v254, 52
	s_cbranch_scc1 .LBB0_1059
	s_barrier
